# v130 + hand-written next-item prefetch in GDN prep for prompt units (tile decomposition hoisted out of the item loop, head constants not reloaded)
# speedup vs baseline: 1.0121x; 1.0121x over previous
.LBB0_511:
	s_add_u32 s34, s20, 0x10c40000
	s_addc_u32 s35, s21, 0
	s_add_u32 s46, s66, 0x1800
	s_addc_u32 s47, s67, 0
	s_add_u32 s62, s66, 0x3000
	s_addc_u32 s63, s67, 0
	s_add_u32 s64, s66, 0x4800
	s_addc_u32 s65, s67, 0
	s_add_u32 s29, s20, 0x13148000
	s_addc_u32 s74, s21, 0
	s_add_u32 s75, s20, 0x15248000
	s_addc_u32 s76, s21, 0
	s_add_u32 s77, s20, 0x11048000
	v_mov_b32_e32 v28, 0
	s_addc_u32 s78, s21, 0
	s_mov_b32 s69, 0
	s_mov_b32 s79, 0x7a44c6b
	s_movk_i32 s80, 0xfde8
	s_movk_i32 s81, 0x480
	s_movk_i32 s82, 0x90
	s_mov_b32 s83, 0x3f2aaaab
	v_mov_b32_e32 v154, 0x3ecc95a3
	s_mov_b32 s84, 0x3f317218
	s_mov_b32 s85, 0x7f800000
	s_mov_b32 s86, 0x33800000
	s_movk_i32 s87, 0x37f
	s_mov_b32 s90, 0x800000
	s_movk_i32 s91, 0x240
	s_movk_i32 s92, 0x900
	v_mov_b32_e32 v108, 0x3f317218
	v_mov_b32_e32 v155, 0x7f800000
	v_mov_b32_e32 v156, 0x7fc00000
	v_mov_b32_e32 v157, 0xff800000
	v_mbcnt_hi_u32_b32 v158, -1, v183
	v_mov_b32_e32 v159, 0x6c00
	v_mov_b32_e32 v32, 0
	v_mov_b32_e32 v33, v28
	v_mov_b32_e32 v34, v28
	v_mov_b32_e32 v35, v28
	v_mov_b32_e32 v160, 0x2400
	v_mov_b32_e32 v161, 0x4800
	v_mov_b32_e32 v162, 0x9000
	s_mov_b32 s94, s2
	s_and_b32 s98, s22, 7
	s_cmp_eq_u32 s98, 0
	s_cselect_b32 s98, 1, 0
	s_branch .LBB0_513

.LBB0_529:
	s_andn2_b64 vcc, exec, s[16:17]
	v_mov_b32_e32 v149, v48
	v_mov_b32_e32 v148, v62
	v_mov_b32_e32 v30, v85
	v_mov_b32_e32 v112, v84
	v_mov_b32_e32 v114, v83
	v_mov_b32_e32 v116, v82
	v_mov_b32_e32 v122, v67
	v_mov_b32_e32 v124, v66
	v_mov_b32_e32 v126, v65
	v_mov_b32_e32 v128, v64
	v_mov_b32_e32 v138, v47
	v_mov_b32_e32 v140, v46
	v_mov_b32_e32 v142, v45
	v_mov_b32_e32 v144, v44
	v_mov_b64_e32 v[146:147], v[54:55]
	v_mov_b64_e32 v[150:151], v[50:51]
	v_mov_b64_e32 v[136:137], v[80:81]
	v_mov_b64_e32 v[132:133], v[78:79]
	v_mov_b64_e32 v[134:135], v[68:69]
	v_mov_b64_e32 v[130:131], v[90:91]
	v_mov_b64_e32 v[118:119], v[88:89]
	v_mov_b64_e32 v[120:121], v[86:87]
	v_mov_b32_e32 v164, v99
	v_mov_b32_e32 v163, v98
	v_mov_b32_e32 v165, v97
	v_mov_b32_e32 v166, v100
	v_mov_b32_e32 v113, v71
	v_mov_b32_e32 v31, v75
	v_mov_b32_e32 v117, v73
	v_mov_b32_e32 v115, v77
	v_mov_b32_e32 v125, v53
	v_mov_b32_e32 v123, v59
	v_mov_b32_e32 v129, v57
	v_mov_b32_e32 v127, v61
	v_mov_b32_e32 v141, v37
	v_mov_b32_e32 v139, v41
	v_mov_b32_e32 v145, v39
	v_mov_b32_e32 v143, v43
	s_cbranch_vccnz .LBB0_575
	s_cmp_eq_u32 s98, 1
	s_cbranch_scc0 .Lpf_slow
	s_cmpk_lt_i32 s93, 0x1000
	s_cbranch_scc1 .Lpf_fast
.Lpf_slow:
	s_ashr_i32 s95, s93, 3
	s_and_b32 s68, s93, 7
	s_cmpk_lt_i32 s95, 0x200
	s_cselect_b64 s[24:25], -1, 0
	s_lshl_b32 s16, s95, 4
	s_add_i32 s72, s16, 0x6000
	s_lshl_b32 s73, s95, 6
	s_cmpk_gt_i32 s95, 0x1ff
	s_cselect_b64 s[16:17], -1, 0
	s_and_b64 s[30:31], s[16:17], exec
	s_cselect_b32 s33, 16, 64
	s_cselect_b32 s97, s72, s73
	s_min_i32 s30, s95, 0x200
	s_and_b32 s30, s30, 0x7f
	s_cmp_lg_u32 s30, 0
	s_cselect_b64 s[30:31], -1, 0
	v_lshlrev_b32_e32 v0, 3, v96
	v_mov_b32_e32 v2, v28
	v_mov_b32_e32 v3, v28
	s_and_b64 s[24:25], s[30:31], s[24:25]
	v_and_b32_e32 v42, 56, v0
	v_mov_b32_e32 v0, v28
	v_mov_b32_e32 v1, v28
	v_mov_b64_e32 v[6:7], v[2:3]
	s_lshl_b32 s96, s68, 6
	v_cndmask_b32_e64 v52, 0, 1, s[24:25]
	v_mov_b64_e32 v[4:5], v[0:1]
	s_and_saveexec_b64 s[72:73], s[14:15]
	s_cbranch_execz .LBB0_534
	v_mul_hi_i32 v4, v96, s79
	v_lshrrev_b32_e32 v5, 31, v4
	v_ashrrev_i32_e32 v4, 4, v4
	v_add_u32_e32 v8, v4, v5
	v_mad_i32_i24 v4, v8, s80, v96
	v_ashrrev_i32_e32 v4, 3, v4
	v_add_u32_e32 v9, -3, v4
	v_cmp_gt_u32_e32 vcc, s33, v9
	v_mov_b32_e32 v29, v28
	v_mov_b32_e32 v30, v28
	v_cndmask_b32_e64 v5, 0, 1, vcc
	v_cmp_lt_i32_e32 vcc, 2, v4
	v_mov_b32_e32 v31, v28
	s_nop 0
	v_cndmask_b32_e32 v4, v52, v5, vcc
	v_and_b32_e32 v4, 1, v4
	v_cmp_eq_u32_e32 vcc, 1, v4
	v_mov_b64_e32 v[4:5], v[28:29]
	v_mov_b64_e32 v[6:7], v[30:31]
	s_and_saveexec_b64 s[14:15], vcc
	s_cbranch_execz .LBB0_533
	v_add_u32_e32 v4, s97, v9
	v_ashrrev_i32_e32 v5, 31, v4
	v_lshlrev_b64 v[4:5], 13, v[4:5]
	v_lshlrev_b32_e32 v6, 9, v8
	v_lshl_add_u64 v[4:5], s[20:21], 0, v[4:5]
	v_ashrrev_i32_e32 v7, 31, v6
	v_lshl_add_u64 v[4:5], v[6:7], 1, v[4:5]
	s_lshl_b32 s24, s96, 1
	s_mov_b32 s25, s69
	v_lshl_add_u64 v[4:5], v[4:5], 0, s[24:25]
	v_lshlrev_b32_e32 v6, 1, v42
	v_mov_b32_e32 v7, v28
	v_lshl_add_u64 v[4:5], v[4:5], 0, v[6:7]
	global_load_dwordx4 v[4:7], v[4:5], off nt

.LBB0_574:
	s_or_b64 exec, exec, s[4:5]
	v_mov_b32_e32 v42, v36
	s_branch .LBB0_575
.Lpf_fast:
	s_ashr_i32 s95, s93, 3
	s_and_b32 s68, s93, 7
	s_lshl_b32 s97, s95, 6
	s_and_b32 s30, s95, 0x7f
	s_cmp_lg_u32 s30, 0
	s_cselect_b32 s30, 0, 3
	s_lshl_b32 s72, s97, 13
	s_add_u32 s72, s20, s72
	s_addc_u32 s73, s21, 0
	s_lshl_b32 s33, s68, 7
	s_add_u32 s72, s72, s33
	s_addc_u32 s73, s73, 0
	s_sub_u32 s72, s72, 0x6000
	s_subb_u32 s73, s73, 0
	v_lshrrev_b32_e32 v95, 3, v96
	v_and_b32_e32 v92, 7, v96
	v_lshlrev_b32_e32 v92, 4, v92
	v_lshl_add_u32 v92, v95, 13, v92
	v_add_u32_e32 v93, 0x0, v92
	v_ashrrev_i32_e32 v94, 13, v93
	v_mov_b64_e32 v[4:5], 0
	v_mov_b64_e32 v[6:7], 0
	v_cmp_le_i32_e32 vcc, s30, v94
	s_and_saveexec_b64 s[24:25], vcc
	global_load_dwordx4 v[4:7], v93, s[72:73] nt
	s_mov_b64 exec, s[24:25]
	v_add_u32_e32 v93, 0x40000, v92
	v_ashrrev_i32_e32 v94, 13, v93
	v_mov_b64_e32 v[0:1], 0
	v_mov_b64_e32 v[2:3], 0
	v_cmp_le_i32_e32 vcc, s30, v94
	s_and_saveexec_b64 s[24:25], vcc
	global_load_dwordx4 v[0:3], v93, s[72:73] nt
	s_mov_b64 exec, s[24:25]
	v_mov_b32_e32 v93, 0xffffa400
	v_mov_b32_e32 v94, 0x80000
	v_cmp_gt_u32_e32 vcc, 3, v95
	s_nop 1
	v_cndmask_b32_e32 v93, v93, v94, vcc
	v_add_u32_e32 v93, v93, v92
	v_ashrrev_i32_e32 v94, 13, v93
	v_mov_b64_e32 v[8:9], 0
	v_mov_b64_e32 v[10:11], 0
	v_cmp_le_i32_e32 vcc, s30, v94
	s_and_saveexec_b64 s[24:25], vcc
	global_load_dwordx4 v[8:11], v93, s[72:73] nt
	s_mov_b64 exec, s[24:25]
	v_add_u32_e32 v93, 0x3a400, v92
	v_ashrrev_i32_e32 v94, 13, v93
	v_mov_b64_e32 v[12:13], 0
	v_mov_b64_e32 v[14:15], 0
	v_cmp_le_i32_e32 vcc, s30, v94
	s_and_saveexec_b64 s[24:25], vcc
	global_load_dwordx4 v[12:15], v93, s[72:73] nt
	s_mov_b64 exec, s[24:25]
	v_mov_b32_e32 v93, 0xffff4800
	v_mov_b32_e32 v94, 0x7a400
	v_cmp_gt_u32_e32 vcc, 6, v95
	s_nop 1
	v_cndmask_b32_e32 v93, v93, v94, vcc
	v_add_u32_e32 v93, v93, v92
	v_ashrrev_i32_e32 v94, 13, v93
	v_mov_b64_e32 v[16:17], 0
	v_mov_b64_e32 v[18:19], 0
	v_cmp_le_i32_e32 vcc, s30, v94
	s_and_saveexec_b64 s[24:25], vcc
	global_load_dwordx4 v[16:19], v93, s[72:73] nt
	s_mov_b64 exec, s[24:25]
	v_add_u32_e32 v93, 0x34800, v92
	v_ashrrev_i32_e32 v94, 13, v93
	v_mov_b64_e32 v[20:21], 0
	v_mov_b64_e32 v[22:23], 0
	v_cmp_le_i32_e32 vcc, s30, v94
	s_and_saveexec_b64 s[24:25], vcc
	global_load_dwordx4 v[20:23], v93, s[72:73] nt
	s_mov_b64 exec, s[24:25]
	v_mov_b32_e32 v93, 0x74800
	v_add_u32_e32 v93, v93, v92
	v_mov_b32_e32 v94, 0x80000000
	v_cmp_gt_u32_e32 vcc, 9, v95
	s_nop 1
	v_cndmask_b32_e32 v94, v94, v93, vcc
	v_ashrrev_i32_e32 v94, 13, v94
	v_mov_b64_e32 v[24:25], 0
	v_mov_b64_e32 v[26:27], 0
	v_cmp_le_i32_e32 vcc, s30, v94
	s_and_saveexec_b64 s[24:25], vcc
	global_load_dwordx4 v[24:27], v93, s[72:73] nt
	s_mov_b64 exec, s[24:25]
	v_mov_b32_e32 v164, 0
	v_mov_b32_e32 v163, 0
	v_add_u32_e32 v93, s97, v96
	v_lshlrev_b32_e32 v93, 6, v93
	s_lshl_b32 s33, s68, 2
	v_add_u32_e32 v93, s33, v93
	v_cmp_gt_u32_e32 vcc, 64, v96
	s_and_saveexec_b64 s[24:25], vcc
	global_load_dword v164, v93, s[34:35]
	global_load_dword v163, v93, s[34:35] offset:32
	s_mov_b64 exec, s[24:25]
	v_mov_b64_e32 v[118:119], 0
	v_mov_b64_e32 v[120:121], 0
	v_mov_b64_e32 v[130:131], 0
	v_mov_b64_e32 v[132:133], 0
	v_mov_b64_e32 v[134:135], 0
	v_mov_b64_e32 v[136:137], 0
	v_mov_b64_e32 v[146:147], 0
	v_mov_b64_e32 v[148:149], 0
	v_mov_b64_e32 v[150:151], 0
	v_mov_b32_e32 v42, v36
